# GEMM-1 tile order: 8-column weight panels (the 64 tiles an XCD runs at once share 8 weight column tiles so the B panel stays L2-resident)
# speedup vs baseline: 1.0050x; 1.0050x over previous
; DEV int bid_() { int b = blockIdx.x; asm volatile("" : "+s"(b)); return b; }
; __device__ void phase_gemm1(PRef p, bf16* sA, bf16* sB) {
;     ...
;   for (int t = bid_() >> 3; t < 36 * 24; t += per_) {
;     int rt = xcd_ + 8 * (t / 24), ct = t % 24;
.LBB0_305:
	s_cmp_eq_u32 s36, 0
	s_cbranch_scc1 .Lg1e_l0
	s_lshr_b32 s13, s25, 1
	s_cmpk_lt_u32 s24, 0x300
	s_cbranch_scc0 .Lg1e_ctx
	s_lshr_b32 s1, s24, 8
	s_and_b32 s0, s24, 0xff
	s_and_b32 s12, s0, 7
	s_lshl_b32 s1, s1, 3
	s_or_b32 s12, s12, s1
	s_lshr_b32 s0, s0, 3
	s_mov_b32 s14, 0xf7fbfdfe
	s_mov_b32 s15, 15
	s_cmp_eq_u32 s13, 1
	s_cselect_b32 s14, 0xdfeff7fb, s14
	s_cmp_eq_u32 s13, 2
	s_cselect_b32 s14, 0x7fbfdfef, s14
	s_cmp_eq_u32 s13, 3
	s_cselect_b32 s14, 0xfeff7fbf, s14
	s_cselect_b32 s15, 13, s15
	s_branch .Lg1e_nth

; DEV int bid_() { int b = blockIdx.x; asm volatile("" : "+s"(b)); return b; }
; __device__ void phase_gemm1(PRef p, bf16* sA, bf16* sB) {
;     ...
;   for (int t = bid_() >> 3; t < 36 * 24; t += per_) {
;     int rt = xcd_ + 8 * (t / 24), ct = t % 24;
.Lg1e_l0:
	s_mov_b32 s1, 0
	s_cmpk_ge_u32 s24, 0x120
	s_cselect_b32 s1, 1, s1
	s_cmpk_ge_u32 s24, 0x240
	s_cselect_b32 s1, 2, s1
	s_mul_i32 s0, s1, 0x120
	s_sub_u32 s0, s24, s0
	s_and_b32 s12, s0, 7
	s_lshl_b32 s1, s1, 3
	s_or_b32 s12, s12, s1
	s_lshr_b32 s0, s0, 3
	s_lshl_b32 s1, s0, 3
	s_or_b32 s10, s1, s25
